# speedup vs baseline: 1.0053x; 1.0053x over previous
; __device__ __forceinline__ unsigned pk2(float lo, float hi) { unsigned r; asm volatile("v_cvt_pk_bf16_f32 %0, %1, %2" : "=v"(r) : "v"(lo), "v"(hi)); return r; }
; __device__ __forceinline__ void ssm_unit(LAS unsigned char* lds, unsigned char* ws, int l, int b, int g, int tid) {
;     ...
;     if (wid == 0) {
;         float ar, ai; lam_pow(p_lr, p_li, __expf(p_ls), 16.f, ar, ai);
;         float xr = 0.f, xi = 0.f;
;         const float* er = ET + (size_t)lane * ECH; const float* ei = ET + (size_t)(64 + lane) * ECH;
;         f32x4 cr[4], ci[4];
; #pragma unroll
;         for (int q = 0; q < 4; ++q) { cr[q] = *(const f32x4*)(er + q * 4); ci[q] = *(const f32x4*)(ei + q * 4); }
; #pragma unroll 1
;         for (int sg = 0; sg < 17; ++sg) {
;             f32x4 nr[4], ni[4];
;             const int sn = sg < 16 ? sg + 1 : 16;
; #pragma unroll
;             for (int q = 0; q < 4; ++q) { nr[q] = *(const f32x4*)(er + sn * 16 + q * 4); ni[q] = *(const f32x4*)(ei + sn * 16 + q * 4); }
; #pragma unroll
;             for (int q = 0; q < 4; ++q)
; #pragma unroll
;                 for (int j = 0; j < 4; ++j) { const int c = sg * 16 + q * 4 + j;
;                     if (c <= 256) { *(unsigned*)(XS + (size_t)c * 128 + 2 * lane) = pk2(xr, xi);
;                         const float tr = ar * xr - ai * xi + cr[q][j], ti = ar * xi + ai * xr + ci[q][j]; xr = tr; xi = ti; } }
; #pragma unroll
;             for (int q = 0; q < 4; ++q) { cr[q] = nr[q]; ci[q] = ni[q]; }
.LBB0_900:
	s_or_b64 exec, exec, s[20:21]
	s_lshl_b64 s[20:21], s[0:1], 2
	s_add_u32 s20, s72, s20
	v_mul_u32_u24_e32 v0, 0x110, v216
	s_addc_u32 s21, s73, s21
	v_lshlrev_b32_e32 v24, 2, v0
	v_lshl_add_u64 v[0:1], s[20:21], 0, v[24:25]
	s_mov_b32 s3, 0x20e9b000
	s_mov_b64 s[20:21], 0x20e9b000
	v_add_co_u32_e32 v2, vcc, s3, v0
	v_lshl_add_u64 v[162:163], v[0:1], 0, s[20:21]
	s_mov_b64 s[20:21], 0x20eac000
	v_addc_co_u32_e32 v3, vcc, 0, v1, vcc
	s_mov_b32 s3, 0x20eac000
	v_lshl_add_u64 v[164:165], v[0:1], 0, s[20:21]
	v_add_co_u32_e32 v0, vcc, s3, v0
	global_load_dwordx4 v[138:141], v[162:163], off offset:32
	global_load_dwordx4 v[146:149], v[162:163], off offset:16
	v_addc_co_u32_e32 v1, vcc, 0, v1, vcc
	global_load_dwordx4 v[154:157], v[2:3], off
	global_load_dwordx4 v[158:161], v[0:1], off
	s_nop 0
	global_load_dwordx4 v[0:3], v[164:165], off offset:48
	global_load_dwordx4 v[142:145], v[164:165], off offset:32
	global_load_dwordx4 v[4:7], v[162:163], off offset:48
	global_load_dwordx4 v[150:153], v[164:165], off offset:16
	v_mul_f32_e32 v9, v211, v10
	v_mul_f32_e32 v9, 0x41800000, v9
	v_mul_f32_e32 v9, 0x3fb8aa3b, v9
	v_exp_f32_e32 v10, v9
	s_mul_i32 s20, s76, 0x11000
	v_readlane_b32 s22, v254, 40
	s_mul_hi_i32 s3, s76, 0x11000
	v_readlane_b32 s23, v254, 41
	s_add_u32 s20, s22, s20
	s_addc_u32 s3, s23, s3
	v_readlane_b32 s21, v254, 28
	v_mov_b32_e32 v9, v11
	s_add_u32 s20, s21, s20
	v_readlane_b32 s21, v254, 29
	v_pk_mul_f32 v[166:167], v[10:11], v[8:9] op_sel_hi:[0,1]
	v_lshlrev_b32_e32 v24, 2, v216
	s_addc_u32 s21, s21, s3
	v_mov_b32_e32 v168, v166
	v_mov_b32_e32 v169, v166
	v_mov_b32_e32 v170, v167
	v_mov_b32_e32 v171, v167
	v_pk_mov_b32 v[172:173], v[166:167], v[166:167] op_sel:[1,0]
	v_lshl_add_u64 v[174:175], s[20:21], 0, v[24:25]
	v_mov_b32_e32 v24, 0
	s_mov_b32 s3, 16
	v_mov_b32_e32 v176, 0
	s_waitcnt vmcnt(0)
	s_branch .LBB0_902
.LBB0_901:
	s_add_i32 s3, s3, 16
	s_waitcnt vmcnt(16)
	v_mov_b64_e32 v[160:161], v[136:137]
	v_mov_b64_e32 v[152:153], v[132:133]
	v_mov_b64_e32 v[144:145], v[128:129]
	v_mov_b64_e32 v[0:1], v[122:123]
	v_mov_b64_e32 v[156:157], v[22:23]
	v_mov_b64_e32 v[148:149], v[18:19]
	v_mov_b64_e32 v[140:141], v[14:15]
	v_mov_b64_e32 v[4:5], v[8:9]
	v_lshl_add_u64 v[174:175], v[174:175], 0, s[18:19]
	s_cmpk_lg_i32 s3, 0x120
	v_mov_b64_e32 v[158:159], v[134:135]
	v_mov_b64_e32 v[150:151], v[130:131]
	v_mov_b64_e32 v[142:143], v[126:127]
	v_mov_b64_e32 v[2:3], v[124:125]
	v_mov_b64_e32 v[154:155], v[20:21]
	v_mov_b64_e32 v[146:147], v[16:17]
	v_mov_b64_e32 v[138:139], v[12:13]
	v_mov_b64_e32 v[6:7], v[10:11]
	v_mov_b32_e32 v24, v177
	s_cbranch_scc0 .LBB0_932
.LBB0_902:
	s_cmpk_lg_i32 s3, 0x110
	s_cselect_b32 s74, s3, 0x100
	s_lshl_b64 s[20:21], s[74:75], 2
	v_lshl_add_u64 v[20:21], v[162:163], 0, s[20:21]
	v_lshl_add_u64 v[134:135], v[164:165], 0, s[20:21]
	global_load_dwordx4 v[8:11], v[20:21], off offset:48
	global_load_dwordx4 v[12:15], v[20:21], off offset:32
	global_load_dwordx4 v[16:19], v[20:21], off offset:16
	s_nop 0
	global_load_dwordx4 v[20:23], v[20:21], off
	s_nop 0
	global_load_dwordx4 v[122:125], v[134:135], off offset:48
	global_load_dwordx4 v[126:129], v[134:135], off offset:32
	global_load_dwordx4 v[130:133], v[134:135], off offset:16
	s_nop 0
	global_load_dwordx4 v[134:137], v[134:135], off
	v_cvt_pk_bf16_f32 v177, v24, v176
	global_store_dword v[174:175], v177, off offset:-2048
	v_pk_mul_f32 v[176:177], v[172:173], v[176:177] op_sel_hi:[1,0]
	s_add_i32 s20, s3, -15
	v_pk_fma_f32 v[178:179], v[166:167], v[24:25], v[176:177] op_sel_hi:[1,0,1] neg_lo:[0,0,1] neg_hi:[0,0,1]
	v_pk_fma_f32 v[176:177], v[166:167], v[24:25], v[176:177] op_sel_hi:[1,0,1]
	v_mov_b32_e32 v178, v158
	v_mov_b32_e32 v177, v179
	v_mov_b32_e32 v179, v154
	s_cmpk_gt_u32 s20, 0x100
	v_pk_add_f32 v[176:177], v[178:179], v[176:177]
	s_cbranch_scc0 .LBB0_917
	s_add_i32 s20, s3, -14
	s_cmpk_gt_u32 s20, 0x100
	s_cbranch_scc0 .LBB0_918

; __device__ __forceinline__ unsigned pk2(float lo, float hi) { unsigned r; asm volatile("v_cvt_pk_bf16_f32 %0, %1, %2" : "=v"(r) : "v"(lo), "v"(hi)); return r; }
; __device__ __forceinline__ void ssm_unit(LAS unsigned char* lds, unsigned char* ws, int l, int b, int g, int tid) {
;     ...
; #pragma unroll
;             for (int q = 0; q < 4; ++q)
; #pragma unroll
;                 for (int j = 0; j < 4; ++j) { const int c = sg * 16 + q * 4 + j;
;                     if (c <= 256) { *(unsigned*)(XS + (size_t)c * 128 + 2 * lane) = pk2(xr, xi);
;                         const float tr = ar * xr - ai * xi + cr[q][j], ti = ar * xi + ai * xr + ci[q][j]; xr = tr; xi = ti; } }
.LBB0_920:
	v_pk_mul_f32 v[154:155], v[172:173], v[176:177] op_sel_hi:[1,0]
	v_cvt_pk_bf16_f32 v24, v177, v176
	global_store_dword v[174:175], v24, off offset:-1024
	v_pk_fma_f32 v[156:157], v[166:167], v[176:177], v[154:155] neg_lo:[0,0,1] neg_hi:[0,0,1]
	v_pk_fma_f32 v[154:155], v[166:167], v[176:177], v[154:155] op_sel:[0,1,0]
	v_mov_b32_e32 v156, v150
	v_mov_b32_e32 v155, v157
	v_mov_b32_e32 v157, v146
	v_pk_add_f32 v[154:155], v[156:157], v[154:155]
	s_nop 0
	v_mov_b64_e32 v[176:177], v[154:155]
	s_add_i32 s20, s3, -11
	s_cmpk_gt_u32 s20, 0x100
	s_cbranch_scc1 .LBB0_907
.LBB0_921:
	v_mul_f32_e32 v24, v173, v177
	v_pk_fma_f32 v[154:155], v[172:173], v[176:177], v[24:25] op_sel_hi:[1,1,0]
	v_mul_f32_e32 v24, v166, v176
	v_pk_fma_f32 v[156:157], v[166:167], v[176:177], v[24:25] op_sel_hi:[1,1,0] neg_lo:[0,0,1] neg_hi:[0,0,1]
	v_mov_b32_e32 v146, v151
	v_mov_b32_e32 v155, v157
	v_pk_add_f32 v[146:147], v[146:147], v[154:155]
	v_cvt_pk_bf16_f32 v24, v177, v176
	global_store_dword v[174:175], v24, off offset:-768
	v_mov_b64_e32 v[176:177], v[146:147]
	s_add_i32 s20, s3, -10
	s_cmpk_gt_u32 s20, 0x100
	s_cbranch_scc1 .LBB0_908
.LBB0_922:
	v_pk_mul_f32 v[146:147], v[168:169], v[176:177]
	v_cvt_pk_bf16_f32 v24, v177, v176
	global_store_dword v[174:175], v24, off offset:-512
	v_pk_fma_f32 v[150:151], v[170:171], v[176:177], v[146:147] op_sel:[0,0,1] op_sel_hi:[1,1,0]
	v_pk_fma_f32 v[146:147], v[170:171], v[176:177], v[146:147] op_sel:[0,0,1] op_sel_hi:[1,1,0] neg_lo:[0,0,1] neg_hi:[0,0,1]
	s_nop 0
	v_mov_b32_e32 v151, v147
	v_mov_b32_e32 v146, v152
	v_mov_b32_e32 v147, v148
	v_pk_add_f32 v[146:147], v[146:147], v[150:151]
	s_nop 0
	v_mov_b64_e32 v[176:177], v[146:147]
	s_add_i32 s20, s3, -9
	s_cmpk_gt_u32 s20, 0x100
	s_cbranch_scc1 .LBB0_909
.LBB0_923:
	v_pk_mul_f32 v[146:147], v[168:169], v[176:177]
	v_mov_b32_e32 v148, v153
	v_pk_fma_f32 v[150:151], v[170:171], v[176:177], v[146:147] op_sel:[0,0,1] op_sel_hi:[1,1,0]
	v_pk_fma_f32 v[146:147], v[170:171], v[176:177], v[146:147] op_sel:[0,0,1] op_sel_hi:[1,1,0] neg_lo:[0,0,1] neg_hi:[0,0,1]
	v_cvt_pk_bf16_f32 v24, v177, v176
	global_store_dword v[174:175], v24, off offset:-256
	v_mov_b32_e32 v151, v147
	v_pk_add_f32 v[146:147], v[148:149], v[150:151]
	s_nop 0
	v_mov_b64_e32 v[176:177], v[146:147]
	s_add_i32 s20, s3, -8
	s_cmpk_gt_u32 s20, 0x100
	s_cbranch_scc1 .LBB0_910
.LBB0_924:
	v_pk_mul_f32 v[146:147], v[168:169], v[176:177]
	v_cvt_pk_bf16_f32 v24, v177, v176
	global_store_dword v[174:175], v24, off
	v_pk_fma_f32 v[148:149], v[170:171], v[176:177], v[146:147] op_sel:[0,0,1] op_sel_hi:[1,1,0] neg_lo:[0,0,1] neg_hi:[0,0,1]
	v_pk_fma_f32 v[146:147], v[170:171], v[176:177], v[146:147] op_sel:[0,0,1] op_sel_hi:[1,1,0]
	v_mov_b32_e32 v148, v142
	v_mov_b32_e32 v147, v149
	v_mov_b32_e32 v149, v138
	v_pk_add_f32 v[146:147], v[148:149], v[146:147]
	s_nop 0
	v_mov_b64_e32 v[176:177], v[146:147]
	s_add_i32 s20, s3, -7
	s_cmpk_gt_u32 s20, 0x100
	s_cbranch_scc1 .LBB0_911
.LBB0_925:
	v_pk_mul_f32 v[146:147], v[168:169], v[176:177]
	v_mov_b32_e32 v138, v143
	v_pk_fma_f32 v[148:149], v[170:171], v[176:177], v[146:147] op_sel:[0,0,1] op_sel_hi:[1,1,0] neg_lo:[0,0,1] neg_hi:[0,0,1]
	v_pk_fma_f32 v[146:147], v[170:171], v[176:177], v[146:147] op_sel:[0,0,1] op_sel_hi:[1,1,0]
	v_cvt_pk_bf16_f32 v24, v177, v176
	global_store_dword v[174:175], v24, off offset:256
	v_mov_b32_e32 v147, v149
	v_pk_add_f32 v[138:139], v[138:139], v[146:147]
	s_nop 0
	v_mov_b64_e32 v[176:177], v[138:139]
	s_add_i32 s20, s3, -6
	s_cmpk_gt_u32 s20, 0x100
	s_cbranch_scc1 .LBB0_912
.LBB0_926:
	v_mul_f32_e32 v24, v173, v177
	v_pk_fma_f32 v[138:139], v[172:173], v[176:177], v[24:25] op_sel_hi:[1,1,0]
	v_mul_f32_e32 v24, v166, v176
	v_pk_fma_f32 v[142:143], v[166:167], v[176:177], v[24:25] op_sel_hi:[1,1,0] neg_lo:[0,0,1] neg_hi:[0,0,1]
	v_mov_b32_e32 v146, v144
	v_mov_b32_e32 v147, v140
	v_mov_b32_e32 v139, v143
	v_pk_add_f32 v[138:139], v[146:147], v[138:139]
	v_cvt_pk_bf16_f32 v24, v177, v176
	global_store_dword v[174:175], v24, off offset:512
	v_mov_b64_e32 v[176:177], v[138:139]
	s_add_i32 s20, s3, -5
	s_cmpk_gt_u32 s20, 0x100
	s_cbranch_scc1 .LBB0_913
.LBB0_927:
	v_pk_mul_f32 v[138:139], v[168:169], v[176:177]
	v_mov_b32_e32 v140, v145
	v_pk_fma_f32 v[142:143], v[170:171], v[176:177], v[138:139] op_sel:[0,0,1] op_sel_hi:[1,1,0]
	v_pk_fma_f32 v[138:139], v[170:171], v[176:177], v[138:139] op_sel:[0,0,1] op_sel_hi:[1,1,0] neg_lo:[0,0,1] neg_hi:[0,0,1]
	v_cvt_pk_bf16_f32 v24, v177, v176
	global_store_dword v[174:175], v24, off offset:768
	v_mov_b32_e32 v143, v139
	v_pk_add_f32 v[138:139], v[140:141], v[142:143]
	s_nop 0
	v_mov_b64_e32 v[176:177], v[138:139]
	s_add_i32 s20, s3, -4
	s_cmpk_gt_u32 s20, 0x100
	s_cbranch_scc1 .LBB0_914
.LBB0_928:
	v_pk_mul_f32 v[138:139], v[168:169], v[176:177]
	s_nop 0
	v_pk_fma_f32 v[140:141], v[170:171], v[176:177], v[138:139] op_sel:[0,0,1] op_sel_hi:[1,1,0]
	v_pk_fma_f32 v[138:139], v[170:171], v[176:177], v[138:139] op_sel:[0,0,1] op_sel_hi:[1,1,0] neg_lo:[0,0,1] neg_hi:[0,0,1]
	s_nop 0
	v_mov_b32_e32 v141, v139
	v_mov_b32_e32 v138, v0
	v_mov_b32_e32 v139, v4
	v_pk_add_f32 v[138:139], v[138:139], v[140:141]
	v_cvt_pk_bf16_f32 v0, v177, v176
	global_store_dword v[174:175], v0, off offset:1024
	v_mov_b64_e32 v[176:177], v[138:139]
	s_add_i32 s20, s3, -3
	s_cmpk_gt_u32 s20, 0x100
	s_cbranch_scc1 .LBB0_915
; __device__ __forceinline__ unsigned pk2(float lo, float hi) { unsigned r; asm volatile("v_cvt_pk_bf16_f32 %0, %1, %2" : "=v"(r) : "v"(lo), "v"(hi)); return r; }
; #define SSM_XLOAD(dst, ctq) do { const int c2_ = ((ctq) < 16 ? (ctq) : 16) * 16 + fr, cc2_ = c2_ < 256 ? c2_ : 256; _Pragma("unroll") for (int kk = 0; kk < 4; ++kk) dst[kk] = *(const bf16x8*)(XS + (size_t)cc2_ * 128 + kk * 32 + fq * 8); } while (0)
; __device__ __forceinline__ void ssm_unit(LAS unsigned char* lds, unsigned char* ws, int l, int b, int g, int tid) {
;     ...
; #pragma unroll
;             for (int q = 0; q < 4; ++q)
; #pragma unroll
;                 for (int j = 0; j < 4; ++j) { const int c = sg * 16 + q * 4 + j;
;                     if (c <= 256) { *(unsigned*)(XS + (size_t)c * 128 + 2 * lane) = pk2(xr, xi);
;                         const float tr = ar * xr - ai * xi + cr[q][j], ti = ar * xi + ai * xr + ci[q][j]; xr = tr; xi = ti; } }
;     ...
;     __syncthreads();
;     {
;         bf16x8 xs[4], x1[4], x2[4];
;     ...
;         SSM_XLOAD(xs, 0); SSM_XLOAD(x1, 1); SSM_XLOAD(x2, 2);
; #pragma unroll 1
;         for (int ct = 0; ct < 17; ++ct) {
;             const int c = ct * 16 + fr, cc = c < 256 ? c : 256;
;             bf16x8 xn[4];
;             SSM_XLOAD(xn, ct + 3);
.LBB0_929:
	v_pk_mul_f32 v[138:139], v[168:169], v[176:177]
	v_mov_b32_e32 v4, v1
	v_pk_fma_f32 v[140:141], v[170:171], v[176:177], v[138:139] op_sel:[0,0,1] op_sel_hi:[1,1,0]
	v_pk_fma_f32 v[138:139], v[170:171], v[176:177], v[138:139] op_sel:[0,0,1] op_sel_hi:[1,1,0] neg_lo:[0,0,1] neg_hi:[0,0,1]
	s_nop 0
	v_mov_b32_e32 v141, v139
	v_pk_add_f32 v[0:1], v[4:5], v[140:141]
	v_cvt_pk_bf16_f32 v4, v177, v176
	global_store_dword v[174:175], v4, off offset:1280
	v_mov_b64_e32 v[176:177], v[0:1]
	s_add_i32 s20, s3, -2
	s_cmpk_gt_u32 s20, 0x100
	s_cbranch_scc1 .LBB0_916
.LBB0_930:
	v_pk_mul_f32 v[0:1], v[168:169], v[176:177]
	v_pk_fma_f32 v[4:5], v[170:171], v[176:177], v[0:1] op_sel:[0,0,1] op_sel_hi:[1,1,0]
	v_pk_fma_f32 v[0:1], v[170:171], v[176:177], v[0:1] op_sel:[0,0,1] op_sel_hi:[1,1,0] neg_lo:[0,0,1] neg_hi:[0,0,1]
	s_nop 0
	v_mov_b32_e32 v5, v1
	v_mov_b32_e32 v0, v2
	v_mov_b32_e32 v1, v6
	v_pk_add_f32 v[0:1], v[0:1], v[4:5]
	v_cvt_pk_bf16_f32 v2, v177, v176
	global_store_dword v[174:175], v2, off offset:1536
	v_mov_b64_e32 v[176:177], v[0:1]
	s_add_i32 s20, s3, -1
	s_cmpk_gt_u32 s20, 0x100
	s_cbranch_scc1 .LBB0_901
.LBB0_931:
	v_pk_mul_f32 v[0:1], v[168:169], v[176:177]
	v_mov_b32_e32 v6, v3
	v_pk_fma_f32 v[4:5], v[170:171], v[176:177], v[0:1] op_sel:[0,0,1] op_sel_hi:[1,1,0]
	v_pk_fma_f32 v[0:1], v[170:171], v[176:177], v[0:1] op_sel:[0,0,1] op_sel_hi:[1,1,0] neg_lo:[0,0,1] neg_hi:[0,0,1]
	v_cvt_pk_bf16_f32 v2, v177, v176
	global_store_dword v[174:175], v2, off offset:1792
	v_mov_b32_e32 v5, v1
	v_pk_add_f32 v[0:1], v[6:7], v[4:5]
	s_nop 0
	v_mov_b64_e32 v[176:177], v[0:1]
	s_branch .LBB0_901
.LBB0_932:
	s_waitcnt vmcnt(0)
	s_lshl_b64 s[0:1], s[0:1], 1
	s_add_u32 s0, s72, s0
	s_addc_u32 s1, s73, s1
	s_add_u32 s0, s0, 0x21f9b000
	s_addc_u32 s1, s1, 0
	v_lshlrev_b32_e32 v24, 8, v213
	v_lshl_add_u64 v[0:1], s[0:1], 0, v[24:25]
	v_mov_b32_e32 v211, v25
	v_lshl_add_u64 v[8:9], v[0:1], 0, v[210:211]
	s_movk_i32 s3, 0x2000
	v_add_co_u32_e32 v20, vcc, s3, v8
	v_lshl_add_u64 v[10:11], v[8:9], 0, s[18:19]
	s_nop 0
	v_addc_co_u32_e32 v21, vcc, 0, v9, vcc
	s_mov_b64 s[20:21], 0x2000
	s_barrier
	global_load_dwordx4 v[16:19], v[8:9], off
	global_load_dwordx4 v[12:15], v[8:9], off offset:64
	global_load_dwordx4 v[4:7], v[8:9], off offset:128
	global_load_dwordx4 v[0:3], v[8:9], off offset:192
	global_load_dwordx4 v[122:125], v[10:11], off offset:64
	global_load_dwordx4 v[126:129], v[10:11], off offset:128
	v_lshl_add_u64 v[8:9], v[8:9], 0, s[20:21]
	global_load_dwordx4 v[130:133], v[20:21], off offset:-4096
	global_load_dwordx4 v[134:137], v[20:21], off
	global_load_dwordx4 v[138:141], v[10:11], off offset:192
	global_load_dwordx4 v[142:145], v[8:9], off offset:64
	global_load_dwordx4 v[146:149], v[8:9], off offset:128
	global_load_dwordx4 v[150:153], v[8:9], off offset:192
	s_cmp_lt_u32 s76, 64
	s_cselect_b64 s[20:21], -1, 0
	s_ashr_i32 s3, s2, 31
	v_lshl_add_u64 v[174:175], s[0:1], 0, v[210:211]
	s_lshl_b64 s[0:1], s[2:3], 12
	s_lshl_b32 s2, s24, 5
	s_add_u32 s2, s72, s2
	s_addc_u32 s3, s73, 0
	v_mov_b32_e32 v209, v25
	v_lshl_add_u64 v[8:9], s[2:3], 0, v[208:209]
	s_mov_b64 s[2:3], 0x1fe1b000
	s_cmp_lt_i32 s30, 16
	v_lshl_add_u64 v[176:177], v[8:9], 0, s[2:3]
	s_cselect_b64 s[2:3], -1, 0
	s_cmp_gt_i32 s30, -1
	s_cselect_b64 s[22:23], -1, 0
	s_cmp_lt_i32 s30, 14
	s_cselect_b64 s[24:25], -1, 0
	s_cmp_gt_i32 s30, 1
	s_cselect_b64 s[34:35], -1, 0
	s_cmp_lt_i32 s30, 12
	s_cselect_b64 s[36:37], -1, 0
	s_cmp_gt_i32 s30, 3
	s_cselect_b64 s[38:39], -1, 0
	s_cmp_lt_i32 s30, 10
	s_cselect_b64 s[40:41], -1, 0
	s_cmp_gt_i32 s30, 5
	s_cselect_b64 s[42:43], -1, 0
	s_cmp_lt_i32 s30, 8
	s_cselect_b64 s[44:45], -1, 0
	s_cmp_gt_i32 s30, 7
	s_cselect_b64 s[46:47], -1, 0
	s_cmp_lt_i32 s30, 6
	s_cselect_b64 s[48:49], -1, 0
	s_add_i32 s31, s30, -6
	s_cmp_gt_u32 s31, 3
	s_cselect_b64 s[50:51], -1, 0
	s_cmp_gt_i32 s30, 9
	s_cselect_b64 s[52:53], -1, 0
	s_cmp_lt_i32 s30, 4
	s_cselect_b64 s[54:55], -1, 0
	s_add_i32 s31, s30, -4
	s_cmp_gt_u32 s31, 7
	s_cselect_b64 s[56:57], -1, 0
	s_cmp_gt_i32 s30, 11
	s_cselect_b64 s[58:59], -1, 0
	s_cmp_lt_i32 s30, 2
	s_cselect_b64 s[60:61], -1, 0
	s_add_i32 s31, s30, -2
	s_cmp_gt_u32 s31, 11
	s_cselect_b64 s[62:63], -1, 0
	s_cmp_gt_i32 s30, 13
	s_cselect_b64 s[64:65], -1, 0
	s_add_i32 s67, s30, 0x2000
	s_sub_i32 s71, 0x200f, s30
	s_ashr_i32 s31, s30, 31
	s_ashr_i32 s70, s67, 31
	s_ashr_i32 s72, s71, 31
	s_add_u32 s76, s0, -1
	s_addc_u32 s77, s1, -1
	s_add_u32 s0, s0, s30
	v_lshlrev_b32_e32 v178, 4, v213
	v_mov_b32_e32 v179, v25
	s_addc_u32 s1, s1, s31
	v_lshl_add_u64 v[8:9], s[76:77], 0, v[178:179]
	s_add_u32 s0, s0, -16
	v_mov_b32_e32 v10, s31
	v_subrev_co_u32_e32 v180, vcc, s30, v8
	s_addc_u32 s1, s1, -1
	s_mov_b32 s66, 0
	v_lshl_or_b32 v184, v213, 7, v224
	v_subb_co_u32_e32 v181, vcc, v9, v10, vcc
	v_lshl_add_u64 v[182:183], s[0:1], 0, v[178:179]
	s_mov_b64 s[30:31], 0
	s_branch .LBB0_934
